# ring4+R4 + 2-row attn-finish, insertion padded to a 64-byte multiple so later loops keep their code alignment
# speedup vs baseline: 1.0116x; 1.0116x over previous
.Lfin2_check:
	v_add_u32_e32 v72, s74, v0
	v_cmp_gt_i32_e32 vcc, s0, v72
	s_nop 4
	s_cbranch_vccz .LBB0_189
	v_ashrrev_i32_e32 v1, 31, v0
	v_lshlrev_b64 v[24:25], 12, v[0:1]
	v_lshl_add_u64 v[36:37], v[2:3], 0, v[24:25]
	global_load_dwordx4 v[24:27], v[36:37], off offset:16
	global_load_dwordx4 v[28:31], v[36:37], off
	global_load_dwordx4 v[32:35], v[36:37], off offset:272
	global_load_dwordx4 v[36:39], v[36:37], off offset:256
	v_ashrrev_i32_e32 v73, 31, v72
	v_lshlrev_b64 v[50:51], 12, v[72:73]
	v_lshl_add_u64 v[62:63], v[2:3], 0, v[50:51]
	global_load_dwordx4 v[50:53], v[62:63], off offset:16
	global_load_dwordx4 v[54:57], v[62:63], off
	global_load_dwordx4 v[58:61], v[62:63], off offset:272
	global_load_dwordx4 v[62:65], v[62:63], off offset:256
	s_waitcnt vmcnt(6)
	v_lshlrev_b32_e32 v40, 16, v28
	v_and_b32_e32 v28, 0xffff0000, v28
	s_waitcnt vmcnt(4)
	v_lshlrev_b32_e32 v41, 16, v36
	v_and_b32_e32 v36, 0xffff0000, v36
	v_fma_f32 v40, -v6, v41, v40
	v_fma_f32 v36, -v6, v36, v28
	v_lshlrev_b32_e32 v28, 16, v29
	v_lshlrev_b32_e32 v41, 16, v37
	v_fma_f32 v41, -v6, v41, v28
	v_and_b32_e32 v28, 0xffff0000, v29
	v_and_b32_e32 v29, 0xffff0000, v37
	v_mul_f32_e32 v44, v36, v36
	v_fma_f32 v37, -v6, v29, v28
	v_lshlrev_b32_e32 v28, 16, v30
	v_lshlrev_b32_e32 v29, 16, v38
	v_fmac_f32_e32 v44, v40, v40
	v_fma_f32 v42, -v6, v29, v28
	v_and_b32_e32 v28, 0xffff0000, v30
	v_and_b32_e32 v29, 0xffff0000, v38
	v_fmac_f32_e32 v44, v41, v41
	v_fma_f32 v38, -v6, v29, v28
	v_lshlrev_b32_e32 v28, 16, v31
	v_lshlrev_b32_e32 v29, 16, v39
	v_fmac_f32_e32 v44, v37, v37
	v_fma_f32 v43, -v6, v29, v28
	v_and_b32_e32 v28, 0xffff0000, v31
	v_and_b32_e32 v29, 0xffff0000, v39
	v_fmac_f32_e32 v44, v42, v42
	v_fma_f32 v39, -v6, v29, v28
	v_fmac_f32_e32 v44, v38, v38
	v_and_b32_e32 v28, 0xffff0000, v24
	v_lshlrev_b32_e32 v29, 16, v24
	v_and_b32_e32 v30, 0xffff0000, v32
	v_lshlrev_b32_e32 v31, 16, v32
	v_fmac_f32_e32 v44, v43, v43
	v_pk_fma_f32 v[28:29], v[6:7], v[30:31], v[28:29] neg_lo:[1,0,0] neg_hi:[1,0,0]
	v_fmac_f32_e32 v44, v39, v39
	v_pk_mul_f32 v[30:31], v[28:29], v[28:29]
	s_nop 0
	v_add_f32_e32 v24, v31, v44
	v_add_f32_e32 v32, v30, v24
	v_and_b32_e32 v24, 0xffff0000, v25
	v_lshlrev_b32_e32 v25, 16, v25
	v_and_b32_e32 v30, 0xffff0000, v33
	v_lshlrev_b32_e32 v31, 16, v33
	v_pk_fma_f32 v[30:31], v[6:7], v[30:31], v[24:25] neg_lo:[1,0,0] neg_hi:[1,0,0]
	v_lshlrev_b32_e32 v33, 16, v34
	v_pk_mul_f32 v[24:25], v[30:31], v[30:31]
	s_nop 0
	v_add_f32_e32 v25, v25, v32
	v_add_f32_e32 v44, v24, v25
	v_and_b32_e32 v24, 0xffff0000, v26
	v_lshlrev_b32_e32 v25, 16, v26
	v_and_b32_e32 v32, 0xffff0000, v34
	v_pk_fma_f32 v[32:33], v[6:7], v[32:33], v[24:25] neg_lo:[1,0,0] neg_hi:[1,0,0]
	v_and_b32_e32 v26, 0xffff0000, v35
	v_pk_mul_f32 v[24:25], v[32:33], v[32:33]
	s_nop 0
	v_add_f32_e32 v25, v25, v44
	v_add_f32_e32 v44, v24, v25
	v_and_b32_e32 v24, 0xffff0000, v27
	v_lshlrev_b32_e32 v25, 16, v27
	v_lshlrev_b32_e32 v27, 16, v35
	v_pk_fma_f32 v[34:35], v[6:7], v[26:27], v[24:25] neg_lo:[1,0,0] neg_hi:[1,0,0]
	s_nop 0
	v_pk_mul_f32 v[24:25], v[34:35], v[34:35]
	s_nop 0
	v_add_f32_e32 v25, v25, v44
	v_add_f32_e32 v24, v24, v25
	ds_swizzle_b32 v25, v24 offset:swizzle(SWAP,1)
	s_waitcnt lgkmcnt(0)
	v_add_f32_e32 v24, v24, v25
	ds_swizzle_b32 v25, v24 offset:swizzle(SWAP,2)
	s_waitcnt lgkmcnt(0)
	v_add_f32_e32 v24, v24, v25
	ds_swizzle_b32 v25, v24 offset:swizzle(SWAP,4)
	s_waitcnt lgkmcnt(0)
	v_add_f32_e32 v24, v24, v25
	v_fmamk_f32 v24, v24, 0x3c000000, v169
	v_cmp_gt_f32_e32 vcc, s85, v24
	v_mul_f32_e32 v25, 0x4b800000, v24
	s_nop 0
	v_cndmask_b32_e32 v24, v24, v25, vcc
	v_rsq_f32_e32 v24, v24
	s_nop 0
	v_mul_f32_e32 v25, 0x45800000, v24
	v_cndmask_b32_e32 v44, v24, v25, vcc
	v_mul_f32_e32 v24, v40, v44
	v_mul_f32_e32 v25, v36, v44
	v_mul_f32_e32 v24, v8, v24
	v_mul_f32_e32 v25, v9, v25
	v_cvt_pk_bf16_f32 v24, v24, v25
	v_mul_f32_e32 v25, v29, v44
	v_mul_f32_e32 v26, v28, v44
	v_mul_f32_e32 v25, v16, v25
	v_mul_f32_e32 v26, v17, v26
	v_cvt_pk_bf16_f32 v28, v25, v26
	v_mul_f32_e32 v25, v41, v44
	v_mul_f32_e32 v26, v37, v44
	v_mul_f32_e32 v25, v10, v25
	v_mul_f32_e32 v26, v11, v26
	v_cvt_pk_bf16_f32 v25, v25, v26
	v_mul_f32_e32 v26, v31, v44
	v_mul_f32_e32 v27, v30, v44
	v_mul_f32_e32 v26, v18, v26
	v_mul_f32_e32 v27, v19, v27
	v_cvt_pk_bf16_f32 v29, v26, v27
	v_mul_f32_e32 v26, v42, v44
	v_mul_f32_e32 v27, v38, v44
	v_mul_f32_e32 v26, v12, v26
	v_mul_f32_e32 v27, v13, v27
	v_cvt_pk_bf16_f32 v26, v26, v27
	v_mul_f32_e32 v27, v33, v44
	v_mul_f32_e32 v30, v32, v44
	v_mul_f32_e32 v27, v20, v27
	v_mul_f32_e32 v30, v21, v30
	v_cvt_pk_bf16_f32 v30, v27, v30
	v_mul_f32_e32 v27, v43, v44
	v_mul_f32_e32 v31, v39, v44
	v_mul_f32_e32 v27, v14, v27
	v_mul_f32_e32 v31, v15, v31
	v_cvt_pk_bf16_f32 v27, v27, v31
	v_mul_f32_e32 v31, v35, v44
	v_mul_f32_e32 v32, v34, v44
	v_mul_f32_e32 v31, v22, v31
	v_mul_f32_e32 v32, v23, v32
	v_cvt_pk_bf16_f32 v31, v31, v32
	v_lshlrev_b64 v[32:33], 11, v[0:1]
	v_lshl_add_u64 v[32:33], v[4:5], 0, v[32:33]
	s_waitcnt vmcnt(2)
	v_lshlrev_b32_e32 v66, 16, v54
	v_and_b32_e32 v54, 0xffff0000, v54
	s_waitcnt vmcnt(0)
	v_lshlrev_b32_e32 v67, 16, v62
	v_and_b32_e32 v62, 0xffff0000, v62
	v_fma_f32 v66, -v6, v67, v66
	v_fma_f32 v62, -v6, v62, v54
	v_lshlrev_b32_e32 v54, 16, v55
	v_lshlrev_b32_e32 v67, 16, v63
	v_fma_f32 v67, -v6, v67, v54
	v_and_b32_e32 v54, 0xffff0000, v55
	v_and_b32_e32 v55, 0xffff0000, v63
	v_mul_f32_e32 v70, v62, v62
	v_fma_f32 v63, -v6, v55, v54
	v_lshlrev_b32_e32 v54, 16, v56
	v_lshlrev_b32_e32 v55, 16, v64
	v_fmac_f32_e32 v70, v66, v66
	v_fma_f32 v68, -v6, v55, v54
	v_and_b32_e32 v54, 0xffff0000, v56
	v_and_b32_e32 v55, 0xffff0000, v64
	v_fmac_f32_e32 v70, v67, v67
	v_fma_f32 v64, -v6, v55, v54
	v_lshlrev_b32_e32 v54, 16, v57
	v_lshlrev_b32_e32 v55, 16, v65
	v_fmac_f32_e32 v70, v63, v63
	v_fma_f32 v69, -v6, v55, v54
	v_and_b32_e32 v54, 0xffff0000, v57
	v_and_b32_e32 v55, 0xffff0000, v65
	v_fmac_f32_e32 v70, v68, v68
	v_fma_f32 v65, -v6, v55, v54
	v_fmac_f32_e32 v70, v64, v64
	v_and_b32_e32 v54, 0xffff0000, v50
	v_lshlrev_b32_e32 v55, 16, v50
	v_and_b32_e32 v56, 0xffff0000, v58
	v_lshlrev_b32_e32 v57, 16, v58
	v_fmac_f32_e32 v70, v69, v69
	v_pk_fma_f32 v[54:55], v[6:7], v[56:57], v[54:55] neg_lo:[1,0,0] neg_hi:[1,0,0]
	v_fmac_f32_e32 v70, v65, v65
	v_pk_mul_f32 v[56:57], v[54:55], v[54:55]
	s_nop 0
	v_add_f32_e32 v50, v57, v70
	v_add_f32_e32 v58, v56, v50
	v_and_b32_e32 v50, 0xffff0000, v51
	v_lshlrev_b32_e32 v51, 16, v51
	v_and_b32_e32 v56, 0xffff0000, v59
	v_lshlrev_b32_e32 v57, 16, v59
	v_pk_fma_f32 v[56:57], v[6:7], v[56:57], v[50:51] neg_lo:[1,0,0] neg_hi:[1,0,0]
	v_lshlrev_b32_e32 v59, 16, v60
	v_pk_mul_f32 v[50:51], v[56:57], v[56:57]
	s_nop 0
	v_add_f32_e32 v51, v51, v58
	v_add_f32_e32 v70, v50, v51
	v_and_b32_e32 v50, 0xffff0000, v52
	v_lshlrev_b32_e32 v51, 16, v52
	v_and_b32_e32 v58, 0xffff0000, v60
	v_pk_fma_f32 v[58:59], v[6:7], v[58:59], v[50:51] neg_lo:[1,0,0] neg_hi:[1,0,0]
	v_and_b32_e32 v52, 0xffff0000, v61
	v_pk_mul_f32 v[50:51], v[58:59], v[58:59]
	s_nop 0
	v_add_f32_e32 v51, v51, v70
	v_add_f32_e32 v70, v50, v51
	v_and_b32_e32 v50, 0xffff0000, v53
	v_lshlrev_b32_e32 v51, 16, v53
	v_lshlrev_b32_e32 v53, 16, v61
	v_pk_fma_f32 v[60:61], v[6:7], v[52:53], v[50:51] neg_lo:[1,0,0] neg_hi:[1,0,0]
	s_nop 0
	v_pk_mul_f32 v[50:51], v[60:61], v[60:61]
	s_nop 0
	v_add_f32_e32 v51, v51, v70
	v_add_f32_e32 v50, v50, v51
	ds_swizzle_b32 v51, v50 offset:swizzle(SWAP,1)
	s_waitcnt lgkmcnt(0)
	v_add_f32_e32 v50, v50, v51
	ds_swizzle_b32 v51, v50 offset:swizzle(SWAP,2)
	s_waitcnt lgkmcnt(0)
	v_add_f32_e32 v50, v50, v51
	ds_swizzle_b32 v51, v50 offset:swizzle(SWAP,4)
	s_waitcnt lgkmcnt(0)
	v_add_f32_e32 v50, v50, v51
	v_fmamk_f32 v50, v50, 0x3c000000, v169
	v_cmp_gt_f32_e32 vcc, s85, v50
	v_mul_f32_e32 v51, 0x4b800000, v50
	s_nop 0
	v_cndmask_b32_e32 v50, v50, v51, vcc
	v_rsq_f32_e32 v50, v50
	s_nop 0
	v_mul_f32_e32 v51, 0x45800000, v50
	v_cndmask_b32_e32 v70, v50, v51, vcc
	v_mul_f32_e32 v50, v66, v70
	v_mul_f32_e32 v51, v62, v70
	v_mul_f32_e32 v50, v8, v50
	v_mul_f32_e32 v51, v9, v51
	v_cvt_pk_bf16_f32 v50, v50, v51
	v_mul_f32_e32 v51, v55, v70
	v_mul_f32_e32 v52, v54, v70
	v_mul_f32_e32 v51, v16, v51
	v_mul_f32_e32 v52, v17, v52
	v_cvt_pk_bf16_f32 v54, v51, v52
	v_mul_f32_e32 v51, v67, v70
	v_mul_f32_e32 v52, v63, v70
	v_mul_f32_e32 v51, v10, v51
	v_mul_f32_e32 v52, v11, v52
	v_cvt_pk_bf16_f32 v51, v51, v52
	v_mul_f32_e32 v52, v57, v70
	v_mul_f32_e32 v53, v56, v70
	v_mul_f32_e32 v52, v18, v52
	v_mul_f32_e32 v53, v19, v53
	v_cvt_pk_bf16_f32 v55, v52, v53
	v_mul_f32_e32 v52, v68, v70
	v_mul_f32_e32 v53, v64, v70
	v_mul_f32_e32 v52, v12, v52
	v_mul_f32_e32 v53, v13, v53
	v_cvt_pk_bf16_f32 v52, v52, v53
	v_mul_f32_e32 v53, v59, v70
	v_mul_f32_e32 v56, v58, v70
	v_mul_f32_e32 v53, v20, v53
	v_mul_f32_e32 v56, v21, v56
	v_cvt_pk_bf16_f32 v56, v53, v56
	v_mul_f32_e32 v53, v69, v70
	v_mul_f32_e32 v57, v65, v70
	v_mul_f32_e32 v53, v14, v53
	v_mul_f32_e32 v57, v15, v57
	v_cvt_pk_bf16_f32 v53, v53, v57
	v_mul_f32_e32 v57, v61, v70
	v_mul_f32_e32 v58, v60, v70
	v_mul_f32_e32 v57, v22, v57
	v_mul_f32_e32 v58, v23, v58
	v_cvt_pk_bf16_f32 v57, v57, v58
	v_lshlrev_b64 v[58:59], 11, v[72:73]
	v_lshl_add_u64 v[58:59], v[4:5], 0, v[58:59]
	global_store_dwordx4 v[58:59], v[50:53], off
	global_store_dwordx4 v[58:59], v[54:57], off offset:16
	global_store_dwordx4 v[32:33], v[24:27], off
	global_store_dwordx4 v[32:33], v[28:31], off offset:16
	v_add_u32_e32 v0, s74, v72
	v_cmp_gt_i32_e32 vcc, s0, v0
	s_nop 4
	s_cbranch_vccnz .Lfin2_check
	s_branch .LBB0_190
	s_nop 0
	s_nop 0
	s_nop 0
	s_nop 0
	s_nop 0
	s_nop 0
	s_nop 0
	s_nop 0
	s_nop 0
	s_nop 0
	s_nop 0
	s_nop 0
	s_nop 0
	s_nop 0
	s_nop 0
